# grid barrier: non-leader workgroups spin on TOPGEN directly instead of per-XCC XGEN (one hop less per barrier)
# speedup vs baseline: 1.0156x; 1.0049x over previous
.LBB0_82:
	s_or_b64 exec, exec, s[12:13]
	v_cvt_f32_u32_e32 v4, v2
	s_waitcnt vmcnt(0)
	v_readfirstlane_b32 s0, v3
	v_sub_u32_e32 v3, 0, v2
	v_rcp_iflag_f32_e32 v4, v4
	v_add_u32_e32 v5, s0, v1
	v_mul_f32_e32 v4, 0x4f7ffffe, v4
	v_cvt_u32_f32_e32 v4, v4
	v_mul_lo_u32 v1, v3, v4
	v_mul_hi_u32 v1, v4, v1
	v_add_u32_e32 v1, v4, v1
	v_mul_hi_u32 v1, v5, v1
	v_mul_lo_u32 v3, v1, v2
	v_sub_u32_e32 v3, v5, v3
	v_add_u32_e32 v4, 1, v1
	v_cmp_ge_u32_e32 vcc, v3, v2
	s_nop 1
	v_cndmask_b32_e32 v1, v1, v4, vcc
	v_sub_u32_e32 v4, v3, v2
	v_cndmask_b32_e32 v3, v3, v4, vcc
	v_add_u32_e32 v4, 1, v1
	v_cmp_ge_u32_e32 vcc, v3, v2
	v_add_u32_e32 v3, 1, v5
	s_nop 0
	v_cndmask_b32_e32 v1, v1, v4, vcc
	v_mul_lo_u32 v4, v2, v1
	v_add_u32_e32 v2, v4, v2
	v_cmp_ne_u32_e32 vcc, v3, v2
	s_and_saveexec_b64 s[0:1], vcc
	s_xor_b64 s[10:11], exec, s[0:1]
	s_cbranch_execz .LBB0_96
	s_waitcnt lgkmcnt(0)
	s_add_u32 s16, s6, 0x32d3500
	s_addc_u32 s17, s7, 0
	v_mov_b32_e32 v0, 0
	global_load_dword v0, v0, s[16:17] sc1
	s_waitcnt vmcnt(0)
	v_cmp_eq_u32_e32 vcc, v0, v1
	s_and_saveexec_b64 s[12:13], vcc
	s_cbranch_execz .LBB0_95
	s_add_u32 s14, s6, 0x32d0200
	s_addc_u32 s15, s7, 0
	s_mov_b32 s0, 1
	s_mov_b64 s[18:19], 0
	v_mov_b32_e32 v0, 0
	s_branch .LBB0_86

.LBB0_218:
	s_or_b64 exec, exec, s[12:13]
	v_cvt_f32_u32_e32 v4, v2
	s_waitcnt vmcnt(0)
	v_readfirstlane_b32 s0, v3
	v_sub_u32_e32 v3, 0, v2
	v_rcp_iflag_f32_e32 v4, v4
	v_add_u32_e32 v5, s0, v1
	v_mul_f32_e32 v4, 0x4f7ffffe, v4
	v_cvt_u32_f32_e32 v4, v4
	v_mul_lo_u32 v1, v3, v4
	v_mul_hi_u32 v1, v4, v1
	v_add_u32_e32 v1, v4, v1
	v_mul_hi_u32 v1, v5, v1
	v_mul_lo_u32 v3, v1, v2
	v_sub_u32_e32 v3, v5, v3
	v_add_u32_e32 v4, 1, v1
	v_cmp_ge_u32_e32 vcc, v3, v2
	s_nop 1
	v_cndmask_b32_e32 v1, v1, v4, vcc
	v_sub_u32_e32 v4, v3, v2
	v_cndmask_b32_e32 v3, v3, v4, vcc
	v_add_u32_e32 v4, 1, v1
	v_cmp_ge_u32_e32 vcc, v3, v2
	v_add_u32_e32 v3, 1, v5
	s_nop 0
	v_cndmask_b32_e32 v1, v1, v4, vcc
	v_mul_lo_u32 v4, v2, v1
	v_add_u32_e32 v2, v4, v2
	v_cmp_ne_u32_e32 vcc, v3, v2
	s_and_saveexec_b64 s[0:1], vcc
	s_xor_b64 s[8:9], exec, s[0:1]
	s_cbranch_execz .LBB0_232
	s_waitcnt lgkmcnt(0)
	s_add_u32 s16, s10, 0x32d3500
	s_addc_u32 s17, s11, 0
	v_mov_b32_e32 v0, 0
	global_load_dword v0, v0, s[16:17] sc1
	s_waitcnt vmcnt(0)
	v_cmp_eq_u32_e32 vcc, v0, v1
	s_and_saveexec_b64 s[12:13], vcc
	s_cbranch_execz .LBB0_231
	s_add_u32 s14, s10, 0x32d0200
	s_addc_u32 s15, s11, 0
	s_mov_b32 s0, 1
	s_mov_b64 s[18:19], 0
	v_mov_b32_e32 v0, 0
	s_branch .LBB0_222

.LBB0_501:
	s_or_b64 exec, exec, s[12:13]
	v_cvt_f32_u32_e32 v4, v2
	s_waitcnt vmcnt(0)
	v_readfirstlane_b32 s1, v3
	v_sub_u32_e32 v3, 0, v2
	v_rcp_iflag_f32_e32 v4, v4
	v_add_u32_e32 v5, s1, v1
	v_mul_f32_e32 v4, 0x4f7ffffe, v4
	v_cvt_u32_f32_e32 v4, v4
	v_mul_lo_u32 v1, v3, v4
	v_mul_hi_u32 v1, v4, v1
	v_add_u32_e32 v1, v4, v1
	v_mul_hi_u32 v1, v5, v1
	v_mul_lo_u32 v3, v1, v2
	v_sub_u32_e32 v3, v5, v3
	v_add_u32_e32 v4, 1, v1
	v_cmp_ge_u32_e32 vcc, v3, v2
	s_nop 1
	v_cndmask_b32_e32 v1, v1, v4, vcc
	v_sub_u32_e32 v4, v3, v2
	v_cndmask_b32_e32 v3, v3, v4, vcc
	v_add_u32_e32 v4, 1, v1
	v_cmp_ge_u32_e32 vcc, v3, v2
	v_add_u32_e32 v3, 1, v5
	s_nop 0
	v_cndmask_b32_e32 v1, v1, v4, vcc
	v_mul_lo_u32 v4, v2, v1
	v_add_u32_e32 v2, v4, v2
	v_cmp_ne_u32_e32 vcc, v3, v2
	s_and_saveexec_b64 s[10:11], vcc
	s_xor_b64 s[10:11], exec, s[10:11]
	s_cbranch_execz .LBB0_515
	s_waitcnt lgkmcnt(0)
	s_add_u32 s18, s16, 0x32d3500
	s_addc_u32 s19, s17, 0
	v_mov_b32_e32 v0, 0
	global_load_dword v0, v0, s[18:19] sc1
	s_waitcnt vmcnt(0)
	v_cmp_eq_u32_e32 vcc, v0, v1
	s_and_saveexec_b64 s[12:13], vcc
	s_cbranch_execz .LBB0_514
	s_add_u32 s14, s16, 0x32d0200
	s_addc_u32 s15, s17, 0
	s_mov_b32 s1, 1
	s_mov_b64 s[24:25], 0
	v_mov_b32_e32 v0, 0
	s_branch .LBB0_505

.LBB0_561:
	s_or_b64 exec, exec, s[14:15]
	v_cvt_f32_u32_e32 v4, v2
	s_waitcnt vmcnt(0)
	v_readfirstlane_b32 s1, v3
	v_sub_u32_e32 v3, 0, v2
	v_rcp_iflag_f32_e32 v4, v4
	v_add_u32_e32 v5, s1, v1
	v_mul_f32_e32 v4, 0x4f7ffffe, v4
	v_cvt_u32_f32_e32 v4, v4
	v_mul_lo_u32 v1, v3, v4
	v_mul_hi_u32 v1, v4, v1
	v_add_u32_e32 v1, v4, v1
	v_mul_hi_u32 v1, v5, v1
	v_mul_lo_u32 v3, v1, v2
	v_sub_u32_e32 v3, v5, v3
	v_add_u32_e32 v4, 1, v1
	v_cmp_ge_u32_e32 vcc, v3, v2
	s_nop 1
	v_cndmask_b32_e32 v1, v1, v4, vcc
	v_sub_u32_e32 v4, v3, v2
	v_cndmask_b32_e32 v3, v3, v4, vcc
	v_add_u32_e32 v4, 1, v1
	v_cmp_ge_u32_e32 vcc, v3, v2
	v_add_u32_e32 v3, 1, v5
	s_nop 0
	v_cndmask_b32_e32 v1, v1, v4, vcc
	v_mul_lo_u32 v4, v2, v1
	v_add_u32_e32 v2, v4, v2
	v_cmp_ne_u32_e32 vcc, v3, v2
	s_and_saveexec_b64 s[12:13], vcc
	s_xor_b64 s[12:13], exec, s[12:13]
	s_cbranch_execz .LBB0_575
	s_waitcnt lgkmcnt(0)
	s_add_u32 s18, s6, 0x32d3500
	s_addc_u32 s19, s7, 0
	v_mov_b32_e32 v0, 0
	global_load_dword v0, v0, s[18:19] sc1
	s_waitcnt vmcnt(0)
	v_cmp_eq_u32_e32 vcc, v0, v1
	s_and_saveexec_b64 s[14:15], vcc
	s_cbranch_execz .LBB0_574
	s_add_u32 s16, s6, 0x32d0200
	s_addc_u32 s17, s7, 0
	s_mov_b32 s1, 1
	s_mov_b64 s[24:25], 0
	v_mov_b32_e32 v0, 0
	s_branch .LBB0_565

.LBB0_848:
	s_or_b64 exec, exec, s[10:11]
	v_cvt_f32_u32_e32 v4, v2
	s_waitcnt vmcnt(0)
	v_readfirstlane_b32 s0, v3
	v_sub_u32_e32 v3, 0, v2
	v_rcp_iflag_f32_e32 v4, v4
	v_add_u32_e32 v5, s0, v1
	v_mul_f32_e32 v4, 0x4f7ffffe, v4
	v_cvt_u32_f32_e32 v4, v4
	v_mul_lo_u32 v1, v3, v4
	v_mul_hi_u32 v1, v4, v1
	v_add_u32_e32 v1, v4, v1
	v_mul_hi_u32 v1, v5, v1
	v_mul_lo_u32 v3, v1, v2
	v_sub_u32_e32 v3, v5, v3
	v_add_u32_e32 v4, 1, v1
	v_cmp_ge_u32_e32 vcc, v3, v2
	s_nop 1
	v_cndmask_b32_e32 v1, v1, v4, vcc
	v_sub_u32_e32 v4, v3, v2
	v_cndmask_b32_e32 v3, v3, v4, vcc
	v_add_u32_e32 v4, 1, v1
	v_cmp_ge_u32_e32 vcc, v3, v2
	v_add_u32_e32 v3, 1, v5
	s_nop 0
	v_cndmask_b32_e32 v1, v1, v4, vcc
	v_mul_lo_u32 v4, v2, v1
	v_add_u32_e32 v2, v4, v2
	v_cmp_ne_u32_e32 vcc, v3, v2
	s_and_saveexec_b64 s[0:1], vcc
	s_xor_b64 s[8:9], exec, s[0:1]
	s_cbranch_execz .LBB0_862
	s_waitcnt lgkmcnt(0)
	s_add_u32 s14, s18, 0x32d3500
	s_addc_u32 s15, s19, 0
	v_mov_b32_e32 v0, 0
	global_load_dword v0, v0, s[14:15] sc1
	s_waitcnt vmcnt(0)
	v_cmp_eq_u32_e32 vcc, v0, v1
	s_and_saveexec_b64 s[10:11], vcc
	s_cbranch_execz .LBB0_861
	s_add_u32 s12, s18, 0x32d0200
	s_addc_u32 s13, s19, 0
	s_mov_b32 s0, 1
	s_mov_b64 s[16:17], 0
	v_mov_b32_e32 v0, 0
	s_branch .LBB0_852

.LBB0_938:
	s_or_b64 exec, exec, s[12:13]
	v_cvt_f32_u32_e32 v4, v2
	s_waitcnt vmcnt(0)
	v_readfirstlane_b32 s0, v3
	v_sub_u32_e32 v3, 0, v2
	v_rcp_iflag_f32_e32 v4, v4
	v_add_u32_e32 v5, s0, v1
	v_mul_f32_e32 v4, 0x4f7ffffe, v4
	v_cvt_u32_f32_e32 v4, v4
	v_mul_lo_u32 v1, v3, v4
	v_mul_hi_u32 v1, v4, v1
	v_add_u32_e32 v1, v4, v1
	v_mul_hi_u32 v1, v5, v1
	v_mul_lo_u32 v3, v1, v2
	v_sub_u32_e32 v3, v5, v3
	v_add_u32_e32 v4, 1, v1
	v_cmp_ge_u32_e32 vcc, v3, v2
	s_nop 1
	v_cndmask_b32_e32 v1, v1, v4, vcc
	v_sub_u32_e32 v4, v3, v2
	v_cndmask_b32_e32 v3, v3, v4, vcc
	v_add_u32_e32 v4, 1, v1
	v_cmp_ge_u32_e32 vcc, v3, v2
	v_add_u32_e32 v3, 1, v5
	s_nop 0
	v_cndmask_b32_e32 v1, v1, v4, vcc
	v_mul_lo_u32 v4, v2, v1
	v_add_u32_e32 v2, v4, v2
	v_cmp_ne_u32_e32 vcc, v3, v2
	s_and_saveexec_b64 s[0:1], vcc
	s_xor_b64 s[10:11], exec, s[0:1]
	s_cbranch_execz .LBB0_952
	s_waitcnt lgkmcnt(0)
	s_add_u32 s18, s14, 0x32d3500
	s_addc_u32 s19, s15, 0
	v_mov_b32_e32 v0, 0
	global_load_dword v0, v0, s[18:19] sc1
	s_waitcnt vmcnt(0)
	v_cmp_eq_u32_e32 vcc, v0, v1
	s_and_saveexec_b64 s[12:13], vcc
	s_cbranch_execz .LBB0_951
	s_add_u32 s16, s14, 0x32d0200
	s_addc_u32 s17, s15, 0
	s_mov_b32 s0, 1
	s_mov_b64 s[24:25], 0
	v_mov_b32_e32 v0, 0
	s_branch .LBB0_942

.LBB0_1010:
	s_or_b64 exec, exec, s[16:17]
	v_cvt_f32_u32_e32 v4, v2
	s_waitcnt vmcnt(0)
	v_readfirstlane_b32 s0, v3
	v_sub_u32_e32 v3, 0, v2
	v_rcp_iflag_f32_e32 v4, v4
	v_add_u32_e32 v5, s0, v1
	v_mul_f32_e32 v4, 0x4f7ffffe, v4
	v_cvt_u32_f32_e32 v4, v4
	v_mul_lo_u32 v1, v3, v4
	v_mul_hi_u32 v1, v4, v1
	v_add_u32_e32 v1, v4, v1
	v_mul_hi_u32 v1, v5, v1
	v_mul_lo_u32 v3, v1, v2
	v_sub_u32_e32 v3, v5, v3
	v_add_u32_e32 v4, 1, v1
	v_cmp_ge_u32_e32 vcc, v3, v2
	s_nop 1
	v_cndmask_b32_e32 v1, v1, v4, vcc
	v_sub_u32_e32 v4, v3, v2
	v_cndmask_b32_e32 v3, v3, v4, vcc
	v_add_u32_e32 v4, 1, v1
	v_cmp_ge_u32_e32 vcc, v3, v2
	v_add_u32_e32 v3, 1, v5
	s_nop 0
	v_cndmask_b32_e32 v1, v1, v4, vcc
	v_mul_lo_u32 v4, v2, v1
	v_add_u32_e32 v2, v4, v2
	v_cmp_ne_u32_e32 vcc, v3, v2
	s_and_saveexec_b64 s[0:1], vcc
	s_xor_b64 s[12:13], exec, s[0:1]
	s_cbranch_execz .LBB0_1024
	s_waitcnt lgkmcnt(0)
	s_add_u32 s24, s14, 0x32d3500
	s_addc_u32 s25, s15, 0
	v_mov_b32_e32 v0, 0
	global_load_dword v0, v0, s[24:25] sc1
	s_waitcnt vmcnt(0)
	v_cmp_eq_u32_e32 vcc, v0, v1
	s_and_saveexec_b64 s[16:17], vcc
	s_cbranch_execz .LBB0_1023
	s_add_u32 s18, s14, 0x32d0200
	s_addc_u32 s19, s15, 0
	s_mov_b32 s0, 1
	s_mov_b64 s[26:27], 0
	v_mov_b32_e32 v0, 0
	s_branch .LBB0_1014

.LBB0_1100:
	s_or_b64 exec, exec, s[16:17]
	v_cvt_f32_u32_e32 v4, v2
	s_waitcnt vmcnt(0)
	v_readfirstlane_b32 s0, v3
	v_sub_u32_e32 v3, 0, v2
	v_rcp_iflag_f32_e32 v4, v4
	v_add_u32_e32 v5, s0, v1
	v_mul_f32_e32 v4, 0x4f7ffffe, v4
	v_cvt_u32_f32_e32 v4, v4
	v_mul_lo_u32 v1, v3, v4
	v_mul_hi_u32 v1, v4, v1
	v_add_u32_e32 v1, v4, v1
	v_mul_hi_u32 v1, v5, v1
	v_mul_lo_u32 v3, v1, v2
	v_sub_u32_e32 v3, v5, v3
	v_add_u32_e32 v4, 1, v1
	v_cmp_ge_u32_e32 vcc, v3, v2
	s_nop 1
	v_cndmask_b32_e32 v1, v1, v4, vcc
	v_sub_u32_e32 v4, v3, v2
	v_cndmask_b32_e32 v3, v3, v4, vcc
	v_add_u32_e32 v4, 1, v1
	v_cmp_ge_u32_e32 vcc, v3, v2
	v_add_u32_e32 v3, 1, v5
	s_nop 0
	v_cndmask_b32_e32 v1, v1, v4, vcc
	v_mul_lo_u32 v4, v2, v1
	v_add_u32_e32 v2, v4, v2
	v_cmp_ne_u32_e32 vcc, v3, v2
	s_and_saveexec_b64 s[0:1], vcc
	s_xor_b64 s[14:15], exec, s[0:1]
	s_cbranch_execz .LBB0_1114
	s_waitcnt lgkmcnt(0)
	s_add_u32 s24, s12, 0x32d3500
	s_addc_u32 s25, s13, 0
	v_mov_b32_e32 v0, 0
	global_load_dword v0, v0, s[24:25] sc1
	s_waitcnt vmcnt(0)
	v_cmp_eq_u32_e32 vcc, v0, v1
	s_and_saveexec_b64 s[16:17], vcc
	s_cbranch_execz .LBB0_1113
	s_add_u32 s18, s12, 0x32d0200
	s_addc_u32 s19, s13, 0
	s_mov_b32 s0, 1
	s_mov_b64 s[26:27], 0
	v_mov_b32_e32 v0, 0
	s_branch .LBB0_1104

.LBB0_1392:
	s_or_b64 exec, exec, s[16:17]
	v_cvt_f32_u32_e32 v4, v2
	s_waitcnt vmcnt(0)
	v_readfirstlane_b32 s0, v3
	v_sub_u32_e32 v3, 0, v2
	v_rcp_iflag_f32_e32 v4, v4
	v_add_u32_e32 v5, s0, v1
	v_mul_f32_e32 v4, 0x4f7ffffe, v4
	v_cvt_u32_f32_e32 v4, v4
	v_mul_lo_u32 v1, v3, v4
	v_mul_hi_u32 v1, v4, v1
	v_add_u32_e32 v1, v4, v1
	v_mul_hi_u32 v1, v5, v1
	v_mul_lo_u32 v3, v1, v2
	v_sub_u32_e32 v3, v5, v3
	v_add_u32_e32 v4, 1, v1
	v_cmp_ge_u32_e32 vcc, v3, v2
	s_nop 1
	v_cndmask_b32_e32 v1, v1, v4, vcc
	v_sub_u32_e32 v4, v3, v2
	v_cndmask_b32_e32 v3, v3, v4, vcc
	v_add_u32_e32 v4, 1, v1
	v_cmp_ge_u32_e32 vcc, v3, v2
	v_add_u32_e32 v3, 1, v5
	s_nop 0
	v_cndmask_b32_e32 v1, v1, v4, vcc
	v_mul_lo_u32 v4, v2, v1
	v_add_u32_e32 v2, v4, v2
	v_cmp_ne_u32_e32 vcc, v3, v2
	s_and_saveexec_b64 s[0:1], vcc
	s_xor_b64 s[14:15], exec, s[0:1]
	s_cbranch_execz .LBB0_1406
	s_waitcnt lgkmcnt(0)
	s_add_u32 s26, s18, 0x32d3500
	s_addc_u32 s27, s19, 0
	v_mov_b32_e32 v0, 0
	global_load_dword v0, v0, s[26:27] sc1
	s_waitcnt vmcnt(0)
	v_cmp_eq_u32_e32 vcc, v0, v1
	s_and_saveexec_b64 s[16:17], vcc
	s_cbranch_execz .LBB0_1405
	s_add_u32 s24, s18, 0x32d0200
	s_addc_u32 s25, s19, 0
	s_mov_b32 s0, 1
	s_mov_b64 s[28:29], 0
	v_mov_b32_e32 v0, 0
	s_branch .LBB0_1396

.LBB0_1699:
	s_or_b64 exec, exec, s[16:17]
	v_cvt_f32_u32_e32 v4, v2
	s_waitcnt vmcnt(0)
	v_readfirstlane_b32 s1, v3
	v_sub_u32_e32 v3, 0, v2
	v_rcp_iflag_f32_e32 v4, v4
	v_add_u32_e32 v5, s1, v1
	v_mul_f32_e32 v4, 0x4f7ffffe, v4
	v_cvt_u32_f32_e32 v4, v4
	v_mul_lo_u32 v1, v3, v4
	v_mul_hi_u32 v1, v4, v1
	v_add_u32_e32 v1, v4, v1
	v_mul_hi_u32 v1, v5, v1
	v_mul_lo_u32 v3, v1, v2
	v_sub_u32_e32 v3, v5, v3
	v_add_u32_e32 v4, 1, v1
	v_cmp_ge_u32_e32 vcc, v3, v2
	s_nop 1
	v_cndmask_b32_e32 v1, v1, v4, vcc
	v_sub_u32_e32 v4, v3, v2
	v_cndmask_b32_e32 v3, v3, v4, vcc
	v_add_u32_e32 v4, 1, v1
	v_cmp_ge_u32_e32 vcc, v3, v2
	v_add_u32_e32 v3, 1, v5
	s_nop 0
	v_cndmask_b32_e32 v1, v1, v4, vcc
	v_mul_lo_u32 v4, v2, v1
	v_add_u32_e32 v2, v4, v2
	v_cmp_ne_u32_e32 vcc, v3, v2
	s_and_saveexec_b64 s[14:15], vcc
	s_xor_b64 s[14:15], exec, s[14:15]
	s_cbranch_execz .LBB0_1713
	s_waitcnt lgkmcnt(0)
	s_add_u32 s24, s30, 0x32d3500
	s_addc_u32 s25, s31, 0
	v_mov_b32_e32 v0, 0
	global_load_dword v0, v0, s[24:25] sc1
	s_waitcnt vmcnt(0)
	v_cmp_eq_u32_e32 vcc, v0, v1
	s_and_saveexec_b64 s[16:17], vcc
	s_cbranch_execz .LBB0_1712
	s_add_u32 s18, s30, 0x32d0200
	s_addc_u32 s19, s31, 0
	s_mov_b32 s1, 1
	s_mov_b64 s[26:27], 0
	v_mov_b32_e32 v0, 0
	s_branch .LBB0_1703

.LBB0_1842:
	s_or_b64 exec, exec, s[14:15]
	v_cvt_f32_u32_e32 v4, v2
	s_waitcnt vmcnt(0)
	v_readfirstlane_b32 s0, v3
	v_sub_u32_e32 v3, 0, v2
	v_rcp_iflag_f32_e32 v4, v4
	v_add_u32_e32 v5, s0, v1
	v_mul_f32_e32 v4, 0x4f7ffffe, v4
	v_cvt_u32_f32_e32 v4, v4
	v_mul_lo_u32 v1, v3, v4
	v_mul_hi_u32 v1, v4, v1
	v_add_u32_e32 v1, v4, v1
	v_mul_hi_u32 v1, v5, v1
	v_mul_lo_u32 v3, v1, v2
	v_sub_u32_e32 v3, v5, v3
	v_add_u32_e32 v4, 1, v1
	v_cmp_ge_u32_e32 vcc, v3, v2
	s_nop 1
	v_cndmask_b32_e32 v1, v1, v4, vcc
	v_sub_u32_e32 v4, v3, v2
	v_cndmask_b32_e32 v3, v3, v4, vcc
	v_add_u32_e32 v4, 1, v1
	v_cmp_ge_u32_e32 vcc, v3, v2
	v_add_u32_e32 v3, 1, v5
	s_nop 0
	v_cndmask_b32_e32 v1, v1, v4, vcc
	v_mul_lo_u32 v4, v2, v1
	v_add_u32_e32 v2, v4, v2
	v_cmp_ne_u32_e32 vcc, v3, v2
	s_and_saveexec_b64 s[0:1], vcc
	s_xor_b64 s[12:13], exec, s[0:1]
	s_cbranch_execz .LBB0_1856
	s_waitcnt lgkmcnt(0)
	s_add_u32 s18, s30, 0x32d3500
	s_addc_u32 s19, s31, 0
	v_mov_b32_e32 v0, 0
	global_load_dword v0, v0, s[18:19] sc1
	s_waitcnt vmcnt(0)
	v_cmp_eq_u32_e32 vcc, v0, v1
	s_and_saveexec_b64 s[14:15], vcc
	s_cbranch_execz .LBB0_1855
	s_add_u32 s16, s30, 0x32d0200
	s_addc_u32 s17, s31, 0
	s_mov_b32 s0, 1
	s_mov_b64 s[24:25], 0
	v_mov_b32_e32 v0, 0
	s_branch .LBB0_1846

.LBB0_2004:
	s_or_b64 exec, exec, s[14:15]
	v_cvt_f32_u32_e32 v4, v2
	s_waitcnt vmcnt(0)
	v_readfirstlane_b32 s0, v3
	v_sub_u32_e32 v3, 0, v2
	v_rcp_iflag_f32_e32 v4, v4
	v_add_u32_e32 v5, s0, v1
	v_mul_f32_e32 v4, 0x4f7ffffe, v4
	v_cvt_u32_f32_e32 v4, v4
	v_mul_lo_u32 v1, v3, v4
	v_mul_hi_u32 v1, v4, v1
	v_add_u32_e32 v1, v4, v1
	v_mul_hi_u32 v1, v5, v1
	v_mul_lo_u32 v3, v1, v2
	v_sub_u32_e32 v3, v5, v3
	v_add_u32_e32 v4, 1, v1
	v_cmp_ge_u32_e32 vcc, v3, v2
	s_nop 1
	v_cndmask_b32_e32 v1, v1, v4, vcc
	v_sub_u32_e32 v4, v3, v2
	v_cndmask_b32_e32 v3, v3, v4, vcc
	v_add_u32_e32 v4, 1, v1
	v_cmp_ge_u32_e32 vcc, v3, v2
	v_add_u32_e32 v3, 1, v5
	s_nop 0
	v_cndmask_b32_e32 v1, v1, v4, vcc
	v_mul_lo_u32 v4, v2, v1
	v_add_u32_e32 v2, v4, v2
	v_cmp_ne_u32_e32 vcc, v3, v2
	s_and_saveexec_b64 s[0:1], vcc
	s_xor_b64 s[10:11], exec, s[0:1]
	s_cbranch_execz .LBB0_2018
	s_waitcnt lgkmcnt(0)
	s_add_u32 s18, s12, 0x32d3500
	s_addc_u32 s19, s13, 0
	v_mov_b32_e32 v0, 0
	global_load_dword v0, v0, s[18:19] sc1
	s_waitcnt vmcnt(0)
	v_cmp_eq_u32_e32 vcc, v0, v1
	s_and_saveexec_b64 s[14:15], vcc
	s_cbranch_execz .LBB0_2017
	s_add_u32 s16, s12, 0x32d0200
	s_addc_u32 s17, s13, 0
	s_mov_b32 s0, 1
	s_mov_b64 s[24:25], 0
	v_mov_b32_e32 v0, 0
	s_branch .LBB0_2008

.LBB0_2094:
	s_or_b64 exec, exec, s[10:11]
	v_cvt_f32_u32_e32 v4, v2
	s_waitcnt vmcnt(0)
	v_readfirstlane_b32 s0, v3
	v_sub_u32_e32 v3, 0, v2
	v_rcp_iflag_f32_e32 v4, v4
	v_add_u32_e32 v5, s0, v1
	v_mul_f32_e32 v4, 0x4f7ffffe, v4
	v_cvt_u32_f32_e32 v4, v4
	v_mul_lo_u32 v1, v3, v4
	v_mul_hi_u32 v1, v4, v1
	v_add_u32_e32 v1, v4, v1
	v_mul_hi_u32 v1, v5, v1
	v_mul_lo_u32 v3, v1, v2
	v_sub_u32_e32 v3, v5, v3
	v_add_u32_e32 v4, 1, v1
	v_cmp_ge_u32_e32 vcc, v3, v2
	s_nop 1
	v_cndmask_b32_e32 v1, v1, v4, vcc
	v_sub_u32_e32 v4, v3, v2
	v_cndmask_b32_e32 v3, v3, v4, vcc
	v_add_u32_e32 v4, 1, v1
	v_cmp_ge_u32_e32 vcc, v3, v2
	v_add_u32_e32 v3, 1, v5
	s_nop 0
	v_cndmask_b32_e32 v1, v1, v4, vcc
	v_mul_lo_u32 v4, v2, v1
	v_add_u32_e32 v2, v4, v2
	v_cmp_ne_u32_e32 vcc, v3, v2
	s_and_saveexec_b64 s[0:1], vcc
	s_xor_b64 s[6:7], exec, s[0:1]
	s_cbranch_execz .LBB0_2108
	s_waitcnt lgkmcnt(0)
	s_add_u32 s14, s8, 0x32d3500
	s_addc_u32 s15, s9, 0
	v_mov_b32_e32 v0, 0
	global_load_dword v0, v0, s[14:15] sc1
	s_waitcnt vmcnt(0)
	v_cmp_eq_u32_e32 vcc, v0, v1
	s_and_saveexec_b64 s[10:11], vcc
	s_cbranch_execz .LBB0_2107
	s_add_u32 s12, s8, 0x32d0200
	s_addc_u32 s13, s9, 0
	s_mov_b32 s0, 1
	s_mov_b64 s[16:17], 0
	v_mov_b32_e32 v0, 0
	s_branch .LBB0_2098
